# P5 epilogue: whole-line write-through stores via permuted mlp_up rows (same as P1)
# speedup vs baseline: 1.0509x; 1.0061x over previous
; __device__ __forceinline__ void tr_tile(const float* W, int K, int N, int kt, int nt, LAS float* tile, const float* kscale, h16* dst, int mode, h16* dstG) {
;     ...
;     {
;         const int n = tid >> 3, kc = (tid & 7) * 8, gn = n0 + n;
;         if (gn < N) {
;             h16x8 o;
; #pragma unroll
;             for (int j = 0; j < 8; ++j) o[j] = (h16)tile[(kc + j) * 65 + n];
;             h16* d;
;             if (mode == 0) d = dst + (size_t)gn * K;
;             else d = (gn < 2048) ? dst + (size_t)gn * K : (gn < 2064 ? dstG + (size_t)(gn - 2048) * K : dst + (size_t)(gn - 16) * K);
;             *(h16x8*)(d + k0 + kc) = o;
;         }
; __device__ __forceinline__ void late_transposes(const Params& p, LAS unsigned char* lds, int w, int nw) {
;     ...
;         if (r < I_UP) { tr_tile(p.in[28], 1024, 4096, r / 64, r % 64, tile, p.in[27], (h16*)(ws + OFF_WT_UP), 0, nullptr); continue; } r -= I_UP;
.LBB0_189:
	s_waitcnt vmcnt(0)
	v_pk_mul_f32 v[0:1], v[4:5], v[18:19] op_sel_hi:[1,0]
	ds_write2_b32 v23, v0, v1 offset1:1
	v_pk_mul_f32 v[0:1], v[6:7], v[18:19] op_sel_hi:[1,0]
	ds_write2_b32 v24, v0, v1 offset1:1
	v_add_u32_e32 v0, s23, v147
	v_cmp_gt_u32_e32 vcc, s31, v0
	s_waitcnt lgkmcnt(0)
	s_barrier
	s_and_saveexec_b64 s[24:25], vcc
	s_cbranch_execz .LBB0_191
	ds_read2_b32 v[2:3], v26 offset0:134 offset1:199
	ds_read2_b32 v[6:7], v26 offset0:4 offset1:69
	ds_read2_b32 v[28:29], v25 offset0:130 offset1:195
	ds_read2_b32 v[30:31], v25 offset1:65
	v_and_b32_e32 v32, 0xe0, v0
	v_lshrrev_b32_e32 v33, 1, v32
	v_lshlrev_b32_e32 v32, 2, v32
	v_and_b32_e32 v32, 0x80, v32
	v_and_b32_e32 v33, 0x60, v33
	v_or_b32_e32 v33, v33, v32
	v_and_b32_e32 v0, 0xffffff1f, v0
	v_or_b32_e32 v0, v0, v33
	v_lshlrev_b32_e32 v8, 11, v0
	v_lshl_add_u64 v[0:1], s[10:11], 0, v[8:9]
	s_mov_b32 s23, s1
	v_lshl_add_u64 v[0:1], s[22:23], 1, v[0:1]
	v_mov_b32_e32 v17, v9
	s_waitcnt lgkmcnt(3)
	v_cvt_pk_f16_f32 v5, v2, v3
	s_waitcnt lgkmcnt(2)
	v_cvt_pk_f16_f32 v4, v6, v7
	s_waitcnt lgkmcnt(1)
	v_cvt_pk_f16_f32 v3, v28, v29
	s_waitcnt lgkmcnt(0)
	v_cvt_pk_f16_f32 v2, v30, v31
	v_lshl_add_u64 v[0:1], v[0:1], 0, v[16:17]
	global_store_dwordx4 v[0:1], v[2:5], off

; #define PG8_STAGE(bufoff, gbase, voff) do { _Pragma("unroll") for (int _i = 0; _i < 2; ++_i) \
;         __builtin_amdgcn_global_load_lds((const unsigned*)((const char*)(gbase) + (voff)[_i]), (LAS unsigned*)(lds + (bufoff) + ldsw + _i * 8192), 16, 0, 0); } while (0)
; #define PG8_LDA(dst, b, h) do { _Pragma("unroll") for (int m = 0; m < 4; ++m) _Pragma("unroll") for (int k = 0; k < 2; ++k) dst[m][k] = *(const LAS h16x8*)(lds + PG8_SA(b, h) + aoff + m * 2048 + k * 1024); } while (0)
; #define PG8_LDB(dst, b, h) do { _Pragma("unroll") for (int n = 0; n < 2; ++n) _Pragma("unroll") for (int k = 0; k < 2; ++k) dst[n][k] = *(const LAS h16x8*)(lds + PG8_SB(b, h) + boff + n * 2048 + k * 1024); } while (0)
; #define PG8_MMA(ai, bj, At, Bt) do { __builtin_amdgcn_s_setprio(1); _Pragma("unroll") for (int m = 0; m < 4; ++m) _Pragma("unroll") for (int n = 0; n < 2; ++n) _Pragma("unroll") for (int k = 0; k < 2; ++k) \
;         acc[ai][bj][m][n] = __builtin_amdgcn_mfma_f32_16x16x32_f16(Bt[n][k], At[m][k], acc[ai][bj][m][n], 0, 0, 0); __builtin_amdgcn_s_setprio(0); } while (0)
; #define PG8_WAIT_L(n) asm volatile("s_waitcnt lgkmcnt(" #n ")" ::: "memory")
; #define PG8_BAR __builtin_amdgcn_s_barrier()
; #define PG8_SCHED __builtin_amdgcn_sched_barrier(0)
; template <class Epi>
; __device__ __forceinline__ void gemm_phase(LAS unsigned char* lds, const Gemm g, const StaticOrder& S, const Epi& E) {
;     ...
;             PG8_LDB(B0, 0, 0); PG8_SCHED; PG8_LDA(At, 0, 0); PG8_STAGE(PG8_SA(1, 1), a1 + hstep, voffA);
;             PG8_WAIT_L(8); PG8_BAR; PG8_WAIT_L(0); PG8_MMA(0, 0, At, B0); PG8_BAR; PG8_SCHED;
;             PG8_LDB(B1, 0, 1); PG8_STAGE(PG8_SB(0, 0), b2, voffB);
;             PG8_BAR; PG8_WAIT_L(0); PG8_MMA(0, 1, At, B1); PG8_BAR;
;             PG8_LDA(At, 0, 1); PG8_STAGE(PG8_SA(0, 0), a2, voffA);
;             PG8_BAR; PG8_WAIT_L(0); PG8_MMA(1, 0, At, B0); PG8_BAR; PG8_SCHED;
.LBB0_483:
	ds_read_b128 v[160:163], v168
	ds_read_b128 v[164:167], v168 offset:1024
	ds_read_b128 v[172:175], v168 offset:2048
	ds_read_b128 v[176:179], v168 offset:3072
	s_add_u32 s36, s0, 0xfffc0080
	s_addc_u32 s37, s1, -1
	s_cmp_eq_u32 s63, 12
	s_cselect_b32 s39, s27, s37
	s_cselect_b32 s38, s59, s36
	s_cselect_b32 s37, s25, s62
	s_cselect_b32 s36, s60, s61
	v_lshl_add_u64 v[212:213], s[0:1], 0, v[152:153]
	s_add_i32 m0, s35, 0xc000
	ds_read_b128 v[180:183], v169
	ds_read_b128 v[184:187], v169 offset:1024
	ds_read_b128 v[188:191], v169 offset:2048
	ds_read_b128 v[192:195], v169 offset:3072
	ds_read_b128 v[196:199], v169 offset:4096
	ds_read_b128 v[200:203], v169 offset:5120
	ds_read_b128 v[204:207], v169 offset:6144
	ds_read_b128 v[208:211], v169 offset:7168
	global_load_lds_dwordx4 v[212:213], off
	v_lshl_add_u64 v[212:213], s[0:1], 0, v[154:155]
	s_add_i32 m0, s35, 0xe000
	s_nop 0
	global_load_lds_dwordx4 v[212:213], off
	s_waitcnt lgkmcnt(8)
	s_barrier
	s_waitcnt lgkmcnt(0)
	s_setprio 1
	s_waitcnt lgkmcnt(0)
	v_mfma_f32_16x16x32_f16 v[124:127], v[160:163], v[180:183], v[124:127]
	v_mfma_f32_16x16x32_f16 v[120:123], v[172:175], v[180:183], v[120:123]
	v_mfma_f32_16x16x32_f16 v[108:111], v[160:163], v[188:191], v[108:111]
	v_mfma_f32_16x16x32_f16 v[104:107], v[172:175], v[188:191], v[104:107]
	v_mfma_f32_16x16x32_f16 v[92:95], v[160:163], v[196:199], v[92:95]
	v_mfma_f32_16x16x32_f16 v[88:91], v[172:175], v[196:199], v[88:91]
	v_mfma_f32_16x16x32_f16 v[76:79], v[160:163], v[204:207], v[76:79]
	v_mfma_f32_16x16x32_f16 v[72:75], v[172:175], v[204:207], v[72:75]
	v_mfma_f32_16x16x32_f16 v[124:127], v[164:167], v[184:187], v[124:127]
	v_mfma_f32_16x16x32_f16 v[120:123], v[176:179], v[184:187], v[120:123]
	v_mfma_f32_16x16x32_f16 v[108:111], v[164:167], v[192:195], v[108:111]
	v_mfma_f32_16x16x32_f16 v[104:107], v[176:179], v[192:195], v[104:107]
	v_mfma_f32_16x16x32_f16 v[92:95], v[164:167], v[200:203], v[92:95]
	v_mfma_f32_16x16x32_f16 v[88:91], v[176:179], v[200:203], v[88:91]
	v_mfma_f32_16x16x32_f16 v[76:79], v[164:167], v[208:211], v[76:79]
	v_mfma_f32_16x16x32_f16 v[72:75], v[176:179], v[208:211], v[72:75]
	s_setprio 0
	s_barrier
	s_add_i32 s64, s51, s44
	v_lshl_add_u64 v[228:229], s[36:37], 0, v[144:145]
	s_mov_b32 m0, s64
	ds_read_b128 v[212:215], v170
	ds_read_b128 v[216:219], v170 offset:1024
	ds_read_b128 v[220:223], v170 offset:2048
	ds_read_b128 v[224:227], v170 offset:3072
	global_load_lds_dwordx4 v[228:229], off
	v_lshl_add_u64 v[230:231], s[36:37], 0, v[150:151]
	s_add_i32 m0, s64, 0x2000
	s_nop 0
	global_load_lds_dwordx4 v[230:231], off
	s_barrier
	s_waitcnt lgkmcnt(0)
	s_setprio 1
	s_waitcnt lgkmcnt(0)
	v_mfma_f32_16x16x32_f16 v[116:119], v[212:215], v[180:183], v[116:119]
	v_mfma_f32_16x16x32_f16 v[112:115], v[220:223], v[180:183], v[112:115]
	v_mfma_f32_16x16x32_f16 v[100:103], v[212:215], v[188:191], v[100:103]
	v_mfma_f32_16x16x32_f16 v[96:99], v[220:223], v[188:191], v[96:99]
	v_mfma_f32_16x16x32_f16 v[84:87], v[212:215], v[196:199], v[84:87]
	v_mfma_f32_16x16x32_f16 v[80:83], v[220:223], v[196:199], v[80:83]
	v_mfma_f32_16x16x32_f16 v[68:71], v[212:215], v[204:207], v[68:71]
	v_mfma_f32_16x16x32_f16 v[64:67], v[220:223], v[204:207], v[64:67]
	v_mfma_f32_16x16x32_f16 v[116:119], v[216:219], v[184:187], v[116:119]
	v_mfma_f32_16x16x32_f16 v[112:115], v[224:227], v[184:187], v[112:115]
	v_mfma_f32_16x16x32_f16 v[100:103], v[216:219], v[192:195], v[100:103]
	v_mfma_f32_16x16x32_f16 v[96:99], v[224:227], v[192:195], v[96:99]
	v_mfma_f32_16x16x32_f16 v[84:87], v[216:219], v[200:203], v[84:87]
	v_mfma_f32_16x16x32_f16 v[80:83], v[224:227], v[200:203], v[80:83]
	v_mfma_f32_16x16x32_f16 v[68:71], v[216:219], v[208:211], v[68:71]
	v_mfma_f32_16x16x32_f16 v[64:67], v[224:227], v[208:211], v[64:67]
	s_setprio 0
	s_mov_b32 m0, s35
	v_lshl_add_u64 v[232:233], s[38:39], 0, v[142:143]
	s_barrier
	ds_read_b128 v[180:183], v169 offset:16384
	ds_read_b128 v[184:187], v169 offset:17408
	ds_read_b128 v[188:191], v169 offset:18432
	ds_read_b128 v[192:195], v169 offset:19456
	ds_read_b128 v[196:199], v169 offset:20480
	ds_read_b128 v[200:203], v169 offset:21504
	ds_read_b128 v[204:207], v169 offset:22528
	ds_read_b128 v[208:211], v169 offset:23552
	global_load_lds_dwordx4 v[232:233], off
	v_lshl_add_u64 v[234:235], s[38:39], 0, v[148:149]
	s_mov_b32 m0, s45
	s_nop 0
	global_load_lds_dwordx4 v[234:235], off
	s_barrier
	s_waitcnt lgkmcnt(0)
	s_setprio 1
	s_waitcnt lgkmcnt(0)
	v_mfma_f32_16x16x32_f16 v[60:63], v[160:163], v[180:183], v[60:63]
	v_mfma_f32_16x16x32_f16 v[56:59], v[172:175], v[180:183], v[56:59]
	v_mfma_f32_16x16x32_f16 v[44:47], v[160:163], v[188:191], v[44:47]
	v_mfma_f32_16x16x32_f16 v[40:43], v[172:175], v[188:191], v[40:43]
	v_mfma_f32_16x16x32_f16 v[28:31], v[160:163], v[196:199], v[28:31]
	v_mfma_f32_16x16x32_f16 v[24:27], v[172:175], v[196:199], v[24:27]
	v_mfma_f32_16x16x32_f16 v[12:15], v[160:163], v[204:207], v[12:15]
	v_mfma_f32_16x16x32_f16 v[8:11], v[172:175], v[204:207], v[8:11]
	v_mfma_f32_16x16x32_f16 v[60:63], v[164:167], v[184:187], v[60:63]
	v_mfma_f32_16x16x32_f16 v[56:59], v[176:179], v[184:187], v[56:59]
	v_mfma_f32_16x16x32_f16 v[44:47], v[164:167], v[192:195], v[44:47]
	v_mfma_f32_16x16x32_f16 v[40:43], v[176:179], v[192:195], v[40:43]
	v_mfma_f32_16x16x32_f16 v[28:31], v[164:167], v[200:203], v[28:31]
	v_mfma_f32_16x16x32_f16 v[24:27], v[176:179], v[200:203], v[24:27]
	v_mfma_f32_16x16x32_f16 v[12:15], v[164:167], v[208:211], v[12:15]
	v_mfma_f32_16x16x32_f16 v[8:11], v[176:179], v[208:211], v[8:11]
	s_setprio 0
	s_barrier
; #define PG8_STAGE(bufoff, gbase, voff) do { _Pragma("unroll") for (int _i = 0; _i < 2; ++_i) \
;         __builtin_amdgcn_global_load_lds((const unsigned*)((const char*)(gbase) + (voff)[_i]), (LAS unsigned*)(lds + (bufoff) + ldsw + _i * 8192), 16, 0, 0); } while (0)
; #define PG8_LDA(dst, b, h) do { _Pragma("unroll") for (int m = 0; m < 4; ++m) _Pragma("unroll") for (int k = 0; k < 2; ++k) dst[m][k] = *(const LAS h16x8*)(lds + PG8_SA(b, h) + aoff + m * 2048 + k * 1024); } while (0)
; #define PG8_LDB(dst, b, h) do { _Pragma("unroll") for (int n = 0; n < 2; ++n) _Pragma("unroll") for (int k = 0; k < 2; ++k) dst[n][k] = *(const LAS h16x8*)(lds + PG8_SB(b, h) + boff + n * 2048 + k * 1024); } while (0)
; #define PG8_MMA(ai, bj, At, Bt) do { __builtin_amdgcn_s_setprio(1); _Pragma("unroll") for (int m = 0; m < 4; ++m) _Pragma("unroll") for (int n = 0; n < 2; ++n) _Pragma("unroll") for (int k = 0; k < 2; ++k) \
;         acc[ai][bj][m][n] = __builtin_amdgcn_mfma_f32_16x16x32_f16(Bt[n][k], At[m][k], acc[ai][bj][m][n], 0, 0, 0); __builtin_amdgcn_s_setprio(0); } while (0)
; #define PG8_WAIT_V(n) asm volatile("s_waitcnt vmcnt(" #n ")" ::: "memory")
; #define PG8_WAIT_L(n) asm volatile("s_waitcnt lgkmcnt(" #n ")" ::: "memory")
; #define PG8_BAR __builtin_amdgcn_s_barrier()
; #define PG8_SCHED __builtin_amdgcn_sched_barrier(0)
; template <class Epi>
; __device__ __forceinline__ void gemm_phase(LAS unsigned char* lds, const Gemm g, const StaticOrder& S, const Epi& E) {
;     ...
;             PG8_STAGE(PG8_SB(0, 1), b2 + hstep, voffB);
;             PG8_WAIT_V(6); PG8_BAR; PG8_MMA(1, 1, At, B1); PG8_BAR;
;             PG8_LDB(B0, 1, 0); PG8_SCHED; PG8_LDA(At, 1, 0); PG8_STAGE(PG8_SA(0, 1), a2 + hstep, voffA);
;             PG8_WAIT_L(8); PG8_BAR; PG8_WAIT_L(0); PG8_MMA(0, 0, At, B0); PG8_BAR; PG8_SCHED;
;             PG8_LDB(B1, 1, 1); PG8_STAGE(PG8_SB(1, 0), b3, voffB);
;             PG8_BAR; PG8_WAIT_L(0); PG8_MMA(0, 1, At, B1); PG8_BAR;
;             PG8_LDA(At, 1, 1); PG8_STAGE(PG8_SA(1, 0), a3, voffA);
	s_add_u32 s64, s36, 0x40000
	s_addc_u32 s65, s37, 0
	s_add_i32 s66, s52, s44
	v_lshl_add_u64 v[160:161], s[64:65], 0, v[144:145]
	s_mov_b32 m0, s66
	s_nop 0
	global_load_lds_dwordx4 v[160:161], off
	v_lshl_add_u64 v[160:161], s[64:65], 0, v[150:151]
	s_add_i32 m0, s66, 0x2000
	s_nop 0
	global_load_lds_dwordx4 v[160:161], off
	s_waitcnt vmcnt(6)
	s_barrier
	s_setprio 1
	v_mfma_f32_16x16x32_f16 v[52:55], v[212:215], v[180:183], v[52:55]
	v_mfma_f32_16x16x32_f16 v[48:51], v[220:223], v[180:183], v[48:51]
	v_mfma_f32_16x16x32_f16 v[36:39], v[212:215], v[188:191], v[36:39]
	v_mfma_f32_16x16x32_f16 v[32:35], v[220:223], v[188:191], v[32:35]
	v_mfma_f32_16x16x32_f16 v[20:23], v[212:215], v[196:199], v[20:23]
	v_mfma_f32_16x16x32_f16 v[16:19], v[220:223], v[196:199], v[16:19]
	v_mfma_f32_16x16x32_f16 v[4:7], v[212:215], v[204:207], v[4:7]
	v_mfma_f32_16x16x32_f16 v[0:3], v[220:223], v[204:207], v[0:3]
	v_mfma_f32_16x16x32_f16 v[52:55], v[216:219], v[184:187], v[52:55]
	v_mfma_f32_16x16x32_f16 v[48:51], v[224:227], v[184:187], v[48:51]
	v_mfma_f32_16x16x32_f16 v[36:39], v[216:219], v[192:195], v[36:39]
	v_mfma_f32_16x16x32_f16 v[32:35], v[224:227], v[192:195], v[32:35]
	v_mfma_f32_16x16x32_f16 v[20:23], v[216:219], v[200:203], v[20:23]
	v_mfma_f32_16x16x32_f16 v[16:19], v[224:227], v[200:203], v[16:19]
	v_mfma_f32_16x16x32_f16 v[4:7], v[216:219], v[208:211], v[4:7]
	v_mfma_f32_16x16x32_f16 v[0:3], v[224:227], v[208:211], v[0:3]
	s_setprio 0
	s_add_i32 s64, 0, 0x18000
	v_add_u32_e32 v176, s64, v141
	s_barrier
	ds_read_b128 v[160:163], v176
	ds_read_b128 v[164:167], v176 offset:1024
	ds_read_b128 v[172:175], v176 offset:2048
	ds_read_b128 v[176:179], v176 offset:3072
	s_add_u32 s38, s38, 0x40000
	s_addc_u32 s39, s39, 0
	s_mov_b32 m0, s46
	v_lshl_add_u64 v[212:213], s[38:39], 0, v[142:143]
	ds_read_b128 v[180:183], v169 offset:32768
	ds_read_b128 v[184:187], v169 offset:33792
	ds_read_b128 v[188:191], v169 offset:34816
	ds_read_b128 v[192:195], v169 offset:35840
	ds_read_b128 v[196:199], v169 offset:36864
	ds_read_b128 v[200:203], v169 offset:37888
	ds_read_b128 v[204:207], v169 offset:38912
	ds_read_b128 v[208:211], v169 offset:39936
	global_load_lds_dwordx4 v[212:213], off
	v_lshl_add_u64 v[212:213], s[38:39], 0, v[148:149]
	s_mov_b32 m0, s47
	s_nop 0
	global_load_lds_dwordx4 v[212:213], off
	s_waitcnt lgkmcnt(8)
	s_barrier
	s_waitcnt lgkmcnt(0)
	s_setprio 1
	s_waitcnt lgkmcnt(0)
	v_mfma_f32_16x16x32_f16 v[124:127], v[160:163], v[180:183], v[124:127]
	v_mfma_f32_16x16x32_f16 v[120:123], v[172:175], v[180:183], v[120:123]
	v_mfma_f32_16x16x32_f16 v[108:111], v[160:163], v[188:191], v[108:111]
	v_mfma_f32_16x16x32_f16 v[104:107], v[172:175], v[188:191], v[104:107]
	v_mfma_f32_16x16x32_f16 v[92:95], v[160:163], v[196:199], v[92:95]
	v_mfma_f32_16x16x32_f16 v[88:91], v[172:175], v[196:199], v[88:91]
	v_mfma_f32_16x16x32_f16 v[76:79], v[160:163], v[204:207], v[76:79]
	v_mfma_f32_16x16x32_f16 v[72:75], v[172:175], v[204:207], v[72:75]
	v_mfma_f32_16x16x32_f16 v[124:127], v[164:167], v[184:187], v[124:127]
	v_mfma_f32_16x16x32_f16 v[120:123], v[176:179], v[184:187], v[120:123]
	v_mfma_f32_16x16x32_f16 v[108:111], v[164:167], v[192:195], v[108:111]
	v_mfma_f32_16x16x32_f16 v[104:107], v[176:179], v[192:195], v[104:107]
	v_mfma_f32_16x16x32_f16 v[92:95], v[164:167], v[200:203], v[92:95]
	v_mfma_f32_16x16x32_f16 v[88:91], v[176:179], v[200:203], v[88:91]
	v_mfma_f32_16x16x32_f16 v[76:79], v[164:167], v[208:211], v[76:79]
	v_mfma_f32_16x16x32_f16 v[72:75], v[176:179], v[208:211], v[72:75]
	s_setprio 0
	s_barrier
	s_add_i32 s38, 0, 0x1c000
	s_add_i32 s39, s64, s44
	v_add_u32_e32 v224, s38, v141
	v_lshl_add_u64 v[228:229], v[228:229], 0, s[8:9]
	s_mov_b32 m0, s39
	ds_read_b128 v[212:215], v224
	ds_read_b128 v[216:219], v224 offset:1024
	ds_read_b128 v[220:223], v224 offset:2048
	ds_read_b128 v[224:227], v224 offset:3072
	global_load_lds_dwordx4 v[228:229], off
	v_lshl_add_u64 v[228:229], v[230:231], 0, s[8:9]
	s_add_i32 m0, s39, 0x2000
	s_nop 0
	global_load_lds_dwordx4 v[228:229], off
	s_barrier
	s_waitcnt lgkmcnt(0)
	s_setprio 1
	s_waitcnt lgkmcnt(0)
	v_mfma_f32_16x16x32_f16 v[116:119], v[212:215], v[180:183], v[116:119]
	v_mfma_f32_16x16x32_f16 v[112:115], v[220:223], v[180:183], v[112:115]
	v_mfma_f32_16x16x32_f16 v[100:103], v[212:215], v[188:191], v[100:103]
	v_mfma_f32_16x16x32_f16 v[96:99], v[220:223], v[188:191], v[96:99]
	v_mfma_f32_16x16x32_f16 v[84:87], v[212:215], v[196:199], v[84:87]
	v_mfma_f32_16x16x32_f16 v[80:83], v[220:223], v[196:199], v[80:83]
	v_mfma_f32_16x16x32_f16 v[68:71], v[212:215], v[204:207], v[68:71]
	v_mfma_f32_16x16x32_f16 v[64:67], v[220:223], v[204:207], v[64:67]
	v_mfma_f32_16x16x32_f16 v[116:119], v[216:219], v[184:187], v[116:119]
	v_mfma_f32_16x16x32_f16 v[112:115], v[224:227], v[184:187], v[112:115]
	v_mfma_f32_16x16x32_f16 v[100:103], v[216:219], v[192:195], v[100:103]
	v_mfma_f32_16x16x32_f16 v[96:99], v[224:227], v[192:195], v[96:99]
	v_mfma_f32_16x16x32_f16 v[84:87], v[216:219], v[200:203], v[84:87]
	v_mfma_f32_16x16x32_f16 v[80:83], v[224:227], v[200:203], v[80:83]
	v_mfma_f32_16x16x32_f16 v[68:71], v[216:219], v[208:211], v[68:71]
	v_mfma_f32_16x16x32_f16 v[64:67], v[224:227], v[208:211], v[64:67]
	s_setprio 0
	s_mov_b32 m0, s49
	v_lshl_add_u64 v[228:229], v[232:233], 0, s[8:9]
	s_barrier
	ds_read_b128 v[180:183], v169 offset:49152
	ds_read_b128 v[184:187], v169 offset:50176
	ds_read_b128 v[188:191], v169 offset:51200
	ds_read_b128 v[192:195], v169 offset:52224
	ds_read_b128 v[196:199], v169 offset:53248
	ds_read_b128 v[200:203], v169 offset:54272
	ds_read_b128 v[204:207], v169 offset:55296
	ds_read_b128 v[208:211], v169 offset:56320
	global_load_lds_dwordx4 v[228:229], off
	v_lshl_add_u64 v[228:229], v[234:235], 0, s[8:9]
	s_mov_b32 m0, s50
	s_nop 0
	global_load_lds_dwordx4 v[228:229], off
	s_barrier
; #define PG8_WAIT_V(n) asm volatile("s_waitcnt vmcnt(" #n ")" ::: "memory")
; #define PG8_WAIT_L(n) asm volatile("s_waitcnt lgkmcnt(" #n ")" ::: "memory")
; #define PG8_BAR __builtin_amdgcn_s_barrier()
; template <class Epi>
; __device__ __forceinline__ void gemm_phase(LAS unsigned char* lds, const Gemm g, const StaticOrder& S, const Epi& E) {
;     ...
;             PG8_BAR; PG8_WAIT_L(0); PG8_MMA(1, 0, At, B0); PG8_BAR; PG8_SCHED;
;             PG8_STAGE(PG8_SB(1, 1), b3 + hstep, voffB);
;             PG8_WAIT_V(6); PG8_BAR; PG8_MMA(1, 1, At, B1); PG8_BAR;
;         }
;     __device__ __forceinline__ void operator()(const f32x4 (&acc)[2][2][4][2], const pg8::Unit& u, int wr, int wc, int fr, int fq) const {
;         const int row0 = u.pm * 256 + wr * 64 + fr, col0 = u.pn * 256 + wc * 32 + 8 * fq;
; #pragma unroll
;         for (int ai = 0; ai < 2; ++ai)
; #pragma unroll
;             for (int m = 0; m < 4; ++m) {
;                 const int row = row0 + ai * 128 + m * 16;
;                 float ss = 0.f, rstd = 1.f;
;                 if (MODE == 2) rstd = rsqrtf(rowss[row] * (1.f / 1024.f) + EPS);
; #pragma unroll
;                 for (int bj = 0; bj < 2; ++bj) {
;                     const int c = col0 + bj * 128;
;                     f32x4 v0 = acc[ai][bj][m][0], v1 = acc[ai][bj][m][1];
;                     if (MODE == 1) {
;                         const float* rp = res + (size_t)row * ldres + c;
;                         v0 += *(const f32x4*)rp; v1 += *(const f32x4*)(rp + 4);
;                     }
;                     if (MODE == 3) {
;                         const h16x8 r8 = *(const h16x8*)(res16 + (size_t)row * ldres + c);
; #pragma unroll
;                         for (int j = 0; j < 4; ++j) { v0[j] += (float)r8[j]; v1[j] += (float)r8[4 + j]; }
;                     }
;                     if (MODE == 1 || MODE == 3) {
;                         ss += v0[0] * v0[0] + v0[1] * v0[1] + v0[2] * v0[2] + v0[3] * v0[3] + v1[0] * v1[0] + v1[1] * v1[1] + v1[2] * v1[2] + v1[3] * v1[3];
;                     }
;                     if (MODE == 2) {
; #pragma unroll
;                         for (int j = 0; j < 4; ++j) { float a = fmaxf(v0[j] * rstd, 0.f), b = fmaxf(v1[j] * rstd, 0.f); v0[j] = a * a; v1[j] = b * b; }
;                     }
;                     *(h16x8*)(o16 + (size_t)row * ld16 + c) = pack8(v0, v1);
	s_waitcnt lgkmcnt(0)
	s_setprio 1
	s_waitcnt lgkmcnt(0)
	v_mfma_f32_16x16x32_f16 v[60:63], v[160:163], v[180:183], v[60:63]
	v_mfma_f32_16x16x32_f16 v[56:59], v[172:175], v[180:183], v[56:59]
	v_mfma_f32_16x16x32_f16 v[44:47], v[160:163], v[188:191], v[44:47]
	v_mfma_f32_16x16x32_f16 v[40:43], v[172:175], v[188:191], v[40:43]
	v_mfma_f32_16x16x32_f16 v[28:31], v[160:163], v[196:199], v[28:31]
	v_mfma_f32_16x16x32_f16 v[24:27], v[172:175], v[196:199], v[24:27]
	v_mfma_f32_16x16x32_f16 v[12:15], v[160:163], v[204:207], v[12:15]
	v_mfma_f32_16x16x32_f16 v[8:11], v[172:175], v[204:207], v[8:11]
	v_mfma_f32_16x16x32_f16 v[60:63], v[164:167], v[184:187], v[60:63]
	v_mfma_f32_16x16x32_f16 v[56:59], v[176:179], v[184:187], v[56:59]
	v_mfma_f32_16x16x32_f16 v[44:47], v[164:167], v[192:195], v[44:47]
	v_mfma_f32_16x16x32_f16 v[40:43], v[176:179], v[192:195], v[40:43]
	v_mfma_f32_16x16x32_f16 v[28:31], v[164:167], v[200:203], v[28:31]
	v_mfma_f32_16x16x32_f16 v[24:27], v[176:179], v[200:203], v[24:27]
	v_mfma_f32_16x16x32_f16 v[12:15], v[164:167], v[208:211], v[12:15]
	v_mfma_f32_16x16x32_f16 v[8:11], v[176:179], v[208:211], v[8:11]
	s_setprio 0
	s_barrier
	s_add_u32 s36, s36, 0x40080
	s_addc_u32 s37, s37, 0
	s_add_i32 s38, s38, s44
	v_lshl_add_u64 v[160:161], s[36:37], 0, v[144:145]
	s_mov_b32 m0, s38
	s_nop 0
	global_load_lds_dwordx4 v[160:161], off
	v_lshl_add_u64 v[160:161], s[36:37], 0, v[150:151]
	s_add_i32 m0, s38, 0x2000
	s_nop 0
	global_load_lds_dwordx4 v[160:161], off
	s_waitcnt vmcnt(6)
	s_barrier
	s_setprio 1
	v_mfma_f32_16x16x32_f16 v[52:55], v[212:215], v[180:183], v[52:55]
	v_mfma_f32_16x16x32_f16 v[48:51], v[220:223], v[180:183], v[48:51]
	v_mfma_f32_16x16x32_f16 v[36:39], v[212:215], v[188:191], v[36:39]
	v_mfma_f32_16x16x32_f16 v[32:35], v[220:223], v[188:191], v[32:35]
	v_mfma_f32_16x16x32_f16 v[20:23], v[212:215], v[196:199], v[20:23]
	v_mfma_f32_16x16x32_f16 v[16:19], v[220:223], v[196:199], v[16:19]
	v_mfma_f32_16x16x32_f16 v[4:7], v[212:215], v[204:207], v[4:7]
	v_mfma_f32_16x16x32_f16 v[0:3], v[220:223], v[204:207], v[0:3]
	v_mfma_f32_16x16x32_f16 v[52:55], v[216:219], v[184:187], v[52:55]
	v_mfma_f32_16x16x32_f16 v[48:51], v[224:227], v[184:187], v[48:51]
	v_mfma_f32_16x16x32_f16 v[36:39], v[216:219], v[192:195], v[36:39]
	v_mfma_f32_16x16x32_f16 v[32:35], v[224:227], v[192:195], v[32:35]
	v_mfma_f32_16x16x32_f16 v[20:23], v[216:219], v[200:203], v[20:23]
	v_mfma_f32_16x16x32_f16 v[16:19], v[224:227], v[200:203], v[16:19]
	v_mfma_f32_16x16x32_f16 v[4:7], v[216:219], v[208:211], v[4:7]
	v_mfma_f32_16x16x32_f16 v[0:3], v[224:227], v[208:211], v[0:3]
	s_setprio 0
	s_add_i32 s63, s63, 2
	s_add_u32 s0, s0, 0x100
	s_addc_u32 s1, s1, 0
	s_add_u32 s61, s61, 0x100
	s_addc_u32 s62, s62, 0
	s_cmp_gt_u32 s63, 13
	s_barrier
	s_cbranch_scc0 .LBB0_483
	v_lshl_add_u32 v166, s34, 8, v139
	v_ashrrev_i32_e32 v167, 31, v166
	v_lshl_add_u64 v[160:161], v[166:167], 2, s[14:15]
	global_load_dword v176, v[160:161], off
	global_load_dword v182, v[160:161], off offset:64
	global_load_dword v183, v[160:161], off offset:128
	global_load_dword v184, v[160:161], off offset:192
	global_load_dword v185, v[160:161], off offset:512
	global_load_dword v186, v[160:161], off offset:576
	global_load_dword v187, v[160:161], off offset:640
	global_load_dword v188, v[160:161], off offset:704
	v_lshl_or_b32 v162, s58, 8, v147
	v_and_b32_e32 v164, 0x60, v147
	v_add_lshl_u32 v162, v162, v164, 1
	v_mov_b32_e32 v163, 0
	v_lshlrev_b64 v[174:175], 13, v[166:167]
	v_lshl_add_u64 v[164:165], s[12:13], 0, v[174:175]
	v_lshl_add_u64 v[164:165], v[164:165], 0, v[162:163]
	s_mov_b32 s58, s24
	s_mov_b32 s34, s26
	s_mov_b64 s[36:37], s[30:31]
	s_mov_b64 s[38:39], s[28:29]
	v_and_b32_e32 v212, 8, v139
	v_cmp_eq_u32_e64 s[98:99], 0, v212
	v_mov_b32_e32 v212, 0xffff0040
	v_cndmask_b32_e64 v214, v212, 0, s[98:99]
	v_cndmask_b32_e64 v215, -1, 0, s[98:99]
	v_mov_b32_e32 v212, 0x10040
	v_cndmask_b32_e64 v216, 0, v212, s[98:99]
	v_mov_b32_e32 v217, 0
	v_mov_b32_e32 v213, 0x358637bd
	s_waitcnt vmcnt(0)
	v_fmamk_f32 v190, v176, 0x3a800000, v213
	v_mul_f32_e32 v191, 0x4b800000, v190
	v_cmp_gt_f32_e64 s[100:101], s53, v190
	s_nop 1
	v_cndmask_b32_e64 v190, v190, v191, s[100:101]
	v_rsq_f32_e32 v190, v190
	s_nop 0
	v_mul_f32_e32 v191, 0x45800000, v190
	v_cndmask_b32_e64 v190, v190, v191, s[100:101]
	v_pk_mul_f32 v[124:125], v[124:125], v[190:191] op_sel_hi:[1,0]
	v_pk_mul_f32 v[126:127], v[126:127], v[190:191] op_sel_hi:[1,0]
	v_pk_mul_f32 v[120:121], v[120:121], v[190:191] op_sel_hi:[1,0]
	v_pk_mul_f32 v[122:123], v[122:123], v[190:191] op_sel_hi:[1,0]
	v_max_f32_e32 v124, 0, v124
	v_max_f32_e32 v125, 0, v125
	v_max_f32_e32 v126, 0, v126
	v_max_f32_e32 v127, 0, v127
	v_max_f32_e32 v120, 0, v120
	v_max_f32_e32 v121, 0, v121
	v_max_f32_e32 v122, 0, v122
	v_max_f32_e32 v123, 0, v123
	v_pk_mul_f32 v[124:125], v[124:125], v[124:125]
	v_pk_mul_f32 v[126:127], v[126:127], v[126:127]
	v_pk_mul_f32 v[120:121], v[120:121], v[120:121]
	v_pk_mul_f32 v[122:123], v[122:123], v[122:123]
	v_cvt_pk_f16_f32 v124, v124, v125
	v_cvt_pk_f16_f32 v125, v126, v127
	v_cvt_pk_f16_f32 v126, v120, v121
	v_cvt_pk_f16_f32 v127, v122, v123
	v_pk_mul_f32 v[116:117], v[116:117], v[190:191] op_sel_hi:[1,0]
	v_pk_mul_f32 v[118:119], v[118:119], v[190:191] op_sel_hi:[1,0]
	v_pk_mul_f32 v[112:113], v[112:113], v[190:191] op_sel_hi:[1,0]
	v_pk_mul_f32 v[114:115], v[114:115], v[190:191] op_sel_hi:[1,0]
	v_max_f32_e32 v116, 0, v116
	v_max_f32_e32 v117, 0, v117
	v_max_f32_e32 v118, 0, v118
	v_max_f32_e32 v119, 0, v119
	v_max_f32_e32 v112, 0, v112
	v_max_f32_e32 v113, 0, v113
	v_max_f32_e32 v114, 0, v114
	v_max_f32_e32 v115, 0, v115
;     __device__ __forceinline__ void operator()(const f32x4 (&acc)[2][2][4][2], const pg8::Unit& u, int wr, int wc, int fr, int fq) const {
;     ...
;         for (int ai = 0; ai < 2; ++ai)
; #pragma unroll
;             for (int m = 0; m < 4; ++m) {
;                 const int row = row0 + ai * 128 + m * 16;
;                 float ss = 0.f, rstd = 1.f;
;                 if (MODE == 2) rstd = rsqrtf(rowss[row] * (1.f / 1024.f) + EPS);
; #pragma unroll
;                 for (int bj = 0; bj < 2; ++bj) {
;                     const int c = col0 + bj * 128;
;                     f32x4 v0 = acc[ai][bj][m][0], v1 = acc[ai][bj][m][1];
;                     if (MODE == 1) {
;                         const float* rp = res + (size_t)row * ldres + c;
;                         v0 += *(const f32x4*)rp; v1 += *(const f32x4*)(rp + 4);
;                     }
;                     if (MODE == 3) {
;                         const h16x8 r8 = *(const h16x8*)(res16 + (size_t)row * ldres + c);
; #pragma unroll
;                         for (int j = 0; j < 4; ++j) { v0[j] += (float)r8[j]; v1[j] += (float)r8[4 + j]; }
;                     }
;                     if (MODE == 1 || MODE == 3) {
;                         ss += v0[0] * v0[0] + v0[1] * v0[1] + v0[2] * v0[2] + v0[3] * v0[3] + v1[0] * v1[0] + v1[1] * v1[1] + v1[2] * v1[2] + v1[3] * v1[3];
;                     }
;                     if (MODE == 2) {
; #pragma unroll
;                         for (int j = 0; j < 4; ++j) { float a = fmaxf(v0[j] * rstd, 0.f), b = fmaxf(v1[j] * rstd, 0.f); v0[j] = a * a; v1[j] = b * b; }
;                     }
;                     *(h16x8*)(o16 + (size_t)row * ld16 + c) = pack8(v0, v1);
	v_pk_mul_f32 v[116:117], v[116:117], v[116:117]
	v_pk_mul_f32 v[118:119], v[118:119], v[118:119]
	v_pk_mul_f32 v[112:113], v[112:113], v[112:113]
	v_pk_mul_f32 v[114:115], v[114:115], v[114:115]
	v_cvt_pk_f16_f32 v116, v116, v117
	v_cvt_pk_f16_f32 v117, v118, v119
	v_cvt_pk_f16_f32 v118, v112, v113
	v_cvt_pk_f16_f32 v119, v114, v115
	s_nop 1
	v_mov_b32_dpp v192, v116 row_ror:8 row_mask:0xf bank_mask:0xf
	v_mov_b32_dpp v193, v117 row_ror:8 row_mask:0xf bank_mask:0xf
	v_mov_b32_dpp v194, v118 row_ror:8 row_mask:0xf bank_mask:0xf
	v_mov_b32_dpp v195, v119 row_ror:8 row_mask:0xf bank_mask:0xf
	v_cndmask_b32_e64 v116, v192, v124, s[98:99]
	v_cndmask_b32_e64 v117, v193, v125, s[98:99]
	v_cndmask_b32_e64 v118, v194, v126, s[98:99]
	v_cndmask_b32_e64 v119, v195, v127, s[98:99]
	v_cndmask_b32_e64 v192, v124, v192, s[98:99]
	v_cndmask_b32_e64 v193, v125, v193, s[98:99]
	v_cndmask_b32_e64 v194, v126, v194, s[98:99]
	v_cndmask_b32_e64 v195, v127, v195, s[98:99]
	v_lshl_add_u64 v[196:197], v[164:165], 0, v[214:215]
	v_lshl_add_u64 v[198:199], v[164:165], 0, v[216:217]
	global_store_dwordx4 v[196:197], v[116:119], off sc0 sc1
	global_store_dwordx4 v[198:199], v[192:195], off sc0 sc1
	s_mov_b32 s100, 0x20000
	s_mov_b32 s101, 0
	v_lshl_add_u64 v[164:165], v[164:165], 0, s[100:101]
	v_fmamk_f32 v190, v182, 0x3a800000, v213
	v_mul_f32_e32 v191, 0x4b800000, v190
	v_cmp_gt_f32_e64 s[100:101], s53, v190
	s_nop 1
	v_cndmask_b32_e64 v190, v190, v191, s[100:101]
	v_rsq_f32_e32 v190, v190
	s_nop 0
	v_mul_f32_e32 v191, 0x45800000, v190
	v_cndmask_b32_e64 v190, v190, v191, s[100:101]
	v_pk_mul_f32 v[108:109], v[108:109], v[190:191] op_sel_hi:[1,0]
	v_pk_mul_f32 v[110:111], v[110:111], v[190:191] op_sel_hi:[1,0]
	v_pk_mul_f32 v[104:105], v[104:105], v[190:191] op_sel_hi:[1,0]
	v_pk_mul_f32 v[106:107], v[106:107], v[190:191] op_sel_hi:[1,0]
	v_max_f32_e32 v108, 0, v108
	v_max_f32_e32 v109, 0, v109
	v_max_f32_e32 v110, 0, v110
	v_max_f32_e32 v111, 0, v111
	v_max_f32_e32 v104, 0, v104
	v_max_f32_e32 v105, 0, v105
	v_max_f32_e32 v106, 0, v106
	v_max_f32_e32 v107, 0, v107
	v_pk_mul_f32 v[108:109], v[108:109], v[108:109]
	v_pk_mul_f32 v[110:111], v[110:111], v[110:111]
	v_pk_mul_f32 v[104:105], v[104:105], v[104:105]
	v_pk_mul_f32 v[106:107], v[106:107], v[106:107]
	v_cvt_pk_f16_f32 v108, v108, v109
	v_cvt_pk_f16_f32 v109, v110, v111
	v_cvt_pk_f16_f32 v110, v104, v105
	v_cvt_pk_f16_f32 v111, v106, v107
	v_pk_mul_f32 v[100:101], v[100:101], v[190:191] op_sel_hi:[1,0]
	v_pk_mul_f32 v[102:103], v[102:103], v[190:191] op_sel_hi:[1,0]
	v_pk_mul_f32 v[96:97], v[96:97], v[190:191] op_sel_hi:[1,0]
	v_pk_mul_f32 v[98:99], v[98:99], v[190:191] op_sel_hi:[1,0]
	v_max_f32_e32 v100, 0, v100
	v_max_f32_e32 v101, 0, v101
	v_max_f32_e32 v102, 0, v102
	v_max_f32_e32 v103, 0, v103
	v_max_f32_e32 v96, 0, v96
	v_max_f32_e32 v97, 0, v97
	v_max_f32_e32 v98, 0, v98
	v_max_f32_e32 v99, 0, v99
	v_pk_mul_f32 v[100:101], v[100:101], v[100:101]
	v_pk_mul_f32 v[102:103], v[102:103], v[102:103]
	v_pk_mul_f32 v[96:97], v[96:97], v[96:97]
	v_pk_mul_f32 v[98:99], v[98:99], v[98:99]
	v_cvt_pk_f16_f32 v100, v100, v101
	v_cvt_pk_f16_f32 v101, v102, v103
	v_cvt_pk_f16_f32 v102, v96, v97
	v_cvt_pk_f16_f32 v103, v98, v99
	s_nop 1
	v_mov_b32_dpp v204, v100 row_ror:8 row_mask:0xf bank_mask:0xf
	v_mov_b32_dpp v205, v101 row_ror:8 row_mask:0xf bank_mask:0xf
	v_mov_b32_dpp v206, v102 row_ror:8 row_mask:0xf bank_mask:0xf
	v_mov_b32_dpp v207, v103 row_ror:8 row_mask:0xf bank_mask:0xf
	v_cndmask_b32_e64 v100, v204, v108, s[98:99]
	v_cndmask_b32_e64 v101, v205, v109, s[98:99]
	v_cndmask_b32_e64 v102, v206, v110, s[98:99]
	v_cndmask_b32_e64 v103, v207, v111, s[98:99]
	v_cndmask_b32_e64 v204, v108, v204, s[98:99]
	v_cndmask_b32_e64 v205, v109, v205, s[98:99]
	v_cndmask_b32_e64 v206, v110, v206, s[98:99]
	v_cndmask_b32_e64 v207, v111, v207, s[98:99]
	v_lshl_add_u64 v[208:209], v[164:165], 0, v[214:215]
	v_lshl_add_u64 v[210:211], v[164:165], 0, v[216:217]
	global_store_dwordx4 v[208:209], v[100:103], off sc0 sc1
	global_store_dwordx4 v[210:211], v[204:207], off sc0 sc1
	s_mov_b32 s100, 0x20000
	s_mov_b32 s101, 0
	v_lshl_add_u64 v[164:165], v[164:165], 0, s[100:101]
	v_fmamk_f32 v190, v183, 0x3a800000, v213
	v_mul_f32_e32 v191, 0x4b800000, v190
	v_cmp_gt_f32_e64 s[100:101], s53, v190
	s_nop 1
	v_cndmask_b32_e64 v190, v190, v191, s[100:101]
	v_rsq_f32_e32 v190, v190
	s_nop 0
	v_mul_f32_e32 v191, 0x45800000, v190
	v_cndmask_b32_e64 v190, v190, v191, s[100:101]
	v_pk_mul_f32 v[92:93], v[92:93], v[190:191] op_sel_hi:[1,0]
	v_pk_mul_f32 v[94:95], v[94:95], v[190:191] op_sel_hi:[1,0]
	v_pk_mul_f32 v[88:89], v[88:89], v[190:191] op_sel_hi:[1,0]
	v_pk_mul_f32 v[90:91], v[90:91], v[190:191] op_sel_hi:[1,0]
	v_max_f32_e32 v92, 0, v92
	v_max_f32_e32 v93, 0, v93
	v_max_f32_e32 v94, 0, v94
	v_max_f32_e32 v95, 0, v95
	v_max_f32_e32 v88, 0, v88
	v_max_f32_e32 v89, 0, v89
	v_max_f32_e32 v90, 0, v90
	v_max_f32_e32 v91, 0, v91
	v_pk_mul_f32 v[92:93], v[92:93], v[92:93]
	v_pk_mul_f32 v[94:95], v[94:95], v[94:95]
	v_pk_mul_f32 v[88:89], v[88:89], v[88:89]
	v_pk_mul_f32 v[90:91], v[90:91], v[90:91]
	v_cvt_pk_f16_f32 v92, v92, v93
	v_cvt_pk_f16_f32 v93, v94, v95
	v_cvt_pk_f16_f32 v94, v88, v89
	v_cvt_pk_f16_f32 v95, v90, v91
	v_pk_mul_f32 v[84:85], v[84:85], v[190:191] op_sel_hi:[1,0]
	v_pk_mul_f32 v[86:87], v[86:87], v[190:191] op_sel_hi:[1,0]
	v_pk_mul_f32 v[80:81], v[80:81], v[190:191] op_sel_hi:[1,0]
	v_pk_mul_f32 v[82:83], v[82:83], v[190:191] op_sel_hi:[1,0]
	v_max_f32_e32 v84, 0, v84
	v_max_f32_e32 v85, 0, v85
	v_max_f32_e32 v86, 0, v86
	v_max_f32_e32 v87, 0, v87
	v_max_f32_e32 v80, 0, v80
	v_max_f32_e32 v81, 0, v81
	v_max_f32_e32 v82, 0, v82
;     __device__ __forceinline__ void operator()(const f32x4 (&acc)[2][2][4][2], const pg8::Unit& u, int wr, int wc, int fr, int fq) const {
;     ...
;         for (int ai = 0; ai < 2; ++ai)
; #pragma unroll
;             for (int m = 0; m < 4; ++m) {
;                 const int row = row0 + ai * 128 + m * 16;
;                 float ss = 0.f, rstd = 1.f;
;                 if (MODE == 2) rstd = rsqrtf(rowss[row] * (1.f / 1024.f) + EPS);
; #pragma unroll
;                 for (int bj = 0; bj < 2; ++bj) {
;                     const int c = col0 + bj * 128;
;                     f32x4 v0 = acc[ai][bj][m][0], v1 = acc[ai][bj][m][1];
;                     if (MODE == 1) {
;                         const float* rp = res + (size_t)row * ldres + c;
;                         v0 += *(const f32x4*)rp; v1 += *(const f32x4*)(rp + 4);
;                     }
;                     if (MODE == 3) {
;                         const h16x8 r8 = *(const h16x8*)(res16 + (size_t)row * ldres + c);
; #pragma unroll
;                         for (int j = 0; j < 4; ++j) { v0[j] += (float)r8[j]; v1[j] += (float)r8[4 + j]; }
;                     }
;                     if (MODE == 1 || MODE == 3) {
;                         ss += v0[0] * v0[0] + v0[1] * v0[1] + v0[2] * v0[2] + v0[3] * v0[3] + v1[0] * v1[0] + v1[1] * v1[1] + v1[2] * v1[2] + v1[3] * v1[3];
;                     }
;                     if (MODE == 2) {
; #pragma unroll
;                         for (int j = 0; j < 4; ++j) { float a = fmaxf(v0[j] * rstd, 0.f), b = fmaxf(v1[j] * rstd, 0.f); v0[j] = a * a; v1[j] = b * b; }
;                     }
;                     *(h16x8*)(o16 + (size_t)row * ld16 + c) = pack8(v0, v1);
	v_max_f32_e32 v83, 0, v83
	v_pk_mul_f32 v[84:85], v[84:85], v[84:85]
	v_pk_mul_f32 v[86:87], v[86:87], v[86:87]
	v_pk_mul_f32 v[80:81], v[80:81], v[80:81]
	v_pk_mul_f32 v[82:83], v[82:83], v[82:83]
	v_cvt_pk_f16_f32 v84, v84, v85
	v_cvt_pk_f16_f32 v85, v86, v87
	v_cvt_pk_f16_f32 v86, v80, v81
	v_cvt_pk_f16_f32 v87, v82, v83
	s_nop 1
	v_mov_b32_dpp v192, v84 row_ror:8 row_mask:0xf bank_mask:0xf
	v_mov_b32_dpp v193, v85 row_ror:8 row_mask:0xf bank_mask:0xf
	v_mov_b32_dpp v194, v86 row_ror:8 row_mask:0xf bank_mask:0xf
	v_mov_b32_dpp v195, v87 row_ror:8 row_mask:0xf bank_mask:0xf
	v_cndmask_b32_e64 v84, v192, v92, s[98:99]
	v_cndmask_b32_e64 v85, v193, v93, s[98:99]
	v_cndmask_b32_e64 v86, v194, v94, s[98:99]
	v_cndmask_b32_e64 v87, v195, v95, s[98:99]
	v_cndmask_b32_e64 v192, v92, v192, s[98:99]
	v_cndmask_b32_e64 v193, v93, v193, s[98:99]
	v_cndmask_b32_e64 v194, v94, v194, s[98:99]
	v_cndmask_b32_e64 v195, v95, v195, s[98:99]
	v_lshl_add_u64 v[196:197], v[164:165], 0, v[214:215]
	v_lshl_add_u64 v[198:199], v[164:165], 0, v[216:217]
	global_store_dwordx4 v[196:197], v[84:87], off sc0 sc1
	global_store_dwordx4 v[198:199], v[192:195], off sc0 sc1
	s_mov_b32 s100, 0x20000
	s_mov_b32 s101, 0
	v_lshl_add_u64 v[164:165], v[164:165], 0, s[100:101]
	v_fmamk_f32 v190, v184, 0x3a800000, v213
	v_mul_f32_e32 v191, 0x4b800000, v190
	v_cmp_gt_f32_e64 s[100:101], s53, v190
	s_nop 1
	v_cndmask_b32_e64 v190, v190, v191, s[100:101]
	v_rsq_f32_e32 v190, v190
	s_nop 0
	v_mul_f32_e32 v191, 0x45800000, v190
	v_cndmask_b32_e64 v190, v190, v191, s[100:101]
	v_pk_mul_f32 v[76:77], v[76:77], v[190:191] op_sel_hi:[1,0]
	v_pk_mul_f32 v[78:79], v[78:79], v[190:191] op_sel_hi:[1,0]
	v_pk_mul_f32 v[72:73], v[72:73], v[190:191] op_sel_hi:[1,0]
	v_pk_mul_f32 v[74:75], v[74:75], v[190:191] op_sel_hi:[1,0]
	v_max_f32_e32 v76, 0, v76
	v_max_f32_e32 v77, 0, v77
	v_max_f32_e32 v78, 0, v78
	v_max_f32_e32 v79, 0, v79
	v_max_f32_e32 v72, 0, v72
	v_max_f32_e32 v73, 0, v73
	v_max_f32_e32 v74, 0, v74
	v_max_f32_e32 v75, 0, v75
	v_pk_mul_f32 v[76:77], v[76:77], v[76:77]
	v_pk_mul_f32 v[78:79], v[78:79], v[78:79]
	v_pk_mul_f32 v[72:73], v[72:73], v[72:73]
	v_pk_mul_f32 v[74:75], v[74:75], v[74:75]
	v_cvt_pk_f16_f32 v76, v76, v77
	v_cvt_pk_f16_f32 v77, v78, v79
	v_cvt_pk_f16_f32 v78, v72, v73
	v_cvt_pk_f16_f32 v79, v74, v75
	v_pk_mul_f32 v[68:69], v[68:69], v[190:191] op_sel_hi:[1,0]
	v_pk_mul_f32 v[70:71], v[70:71], v[190:191] op_sel_hi:[1,0]
	v_pk_mul_f32 v[64:65], v[64:65], v[190:191] op_sel_hi:[1,0]
	v_pk_mul_f32 v[66:67], v[66:67], v[190:191] op_sel_hi:[1,0]
	v_max_f32_e32 v68, 0, v68
	v_max_f32_e32 v69, 0, v69
	v_max_f32_e32 v70, 0, v70
	v_max_f32_e32 v71, 0, v71
	v_max_f32_e32 v64, 0, v64
	v_max_f32_e32 v65, 0, v65
	v_max_f32_e32 v66, 0, v66
	v_max_f32_e32 v67, 0, v67
	v_pk_mul_f32 v[68:69], v[68:69], v[68:69]
	v_pk_mul_f32 v[70:71], v[70:71], v[70:71]
	v_pk_mul_f32 v[64:65], v[64:65], v[64:65]
	v_pk_mul_f32 v[66:67], v[66:67], v[66:67]
	v_cvt_pk_f16_f32 v68, v68, v69
	v_cvt_pk_f16_f32 v69, v70, v71
	v_cvt_pk_f16_f32 v70, v64, v65
	v_cvt_pk_f16_f32 v71, v66, v67
	s_nop 1
	v_mov_b32_dpp v204, v68 row_ror:8 row_mask:0xf bank_mask:0xf
	v_mov_b32_dpp v205, v69 row_ror:8 row_mask:0xf bank_mask:0xf
	v_mov_b32_dpp v206, v70 row_ror:8 row_mask:0xf bank_mask:0xf
	v_mov_b32_dpp v207, v71 row_ror:8 row_mask:0xf bank_mask:0xf
	v_cndmask_b32_e64 v68, v204, v76, s[98:99]
	v_cndmask_b32_e64 v69, v205, v77, s[98:99]
	v_cndmask_b32_e64 v70, v206, v78, s[98:99]
	v_cndmask_b32_e64 v71, v207, v79, s[98:99]
	v_cndmask_b32_e64 v204, v76, v204, s[98:99]
	v_cndmask_b32_e64 v205, v77, v205, s[98:99]
	v_cndmask_b32_e64 v206, v78, v206, s[98:99]
	v_cndmask_b32_e64 v207, v79, v207, s[98:99]
	v_lshl_add_u64 v[208:209], v[164:165], 0, v[214:215]
	v_lshl_add_u64 v[210:211], v[164:165], 0, v[216:217]
	global_store_dwordx4 v[208:209], v[68:71], off sc0 sc1
	global_store_dwordx4 v[210:211], v[204:207], off sc0 sc1
	s_mov_b32 s100, 0xa0000
	s_mov_b32 s101, 0
	v_lshl_add_u64 v[164:165], v[164:165], 0, s[100:101]
	v_fmamk_f32 v190, v185, 0x3a800000, v213
	v_mul_f32_e32 v191, 0x4b800000, v190
	v_cmp_gt_f32_e64 s[100:101], s53, v190
	s_nop 1
	v_cndmask_b32_e64 v190, v190, v191, s[100:101]
	v_rsq_f32_e32 v190, v190
	s_nop 0
	v_mul_f32_e32 v191, 0x45800000, v190
	v_cndmask_b32_e64 v190, v190, v191, s[100:101]
	v_pk_mul_f32 v[60:61], v[60:61], v[190:191] op_sel_hi:[1,0]
	v_pk_mul_f32 v[62:63], v[62:63], v[190:191] op_sel_hi:[1,0]
	v_pk_mul_f32 v[56:57], v[56:57], v[190:191] op_sel_hi:[1,0]
	v_pk_mul_f32 v[58:59], v[58:59], v[190:191] op_sel_hi:[1,0]
	v_max_f32_e32 v60, 0, v60
	v_max_f32_e32 v61, 0, v61
	v_max_f32_e32 v62, 0, v62
	v_max_f32_e32 v63, 0, v63
	v_max_f32_e32 v56, 0, v56
	v_max_f32_e32 v57, 0, v57
	v_max_f32_e32 v58, 0, v58
	v_max_f32_e32 v59, 0, v59
	v_pk_mul_f32 v[60:61], v[60:61], v[60:61]
	v_pk_mul_f32 v[62:63], v[62:63], v[62:63]
	v_pk_mul_f32 v[56:57], v[56:57], v[56:57]
	v_pk_mul_f32 v[58:59], v[58:59], v[58:59]
	v_cvt_pk_f16_f32 v60, v60, v61
	v_cvt_pk_f16_f32 v61, v62, v63
	v_cvt_pk_f16_f32 v62, v56, v57
	v_cvt_pk_f16_f32 v63, v58, v59
	v_pk_mul_f32 v[52:53], v[52:53], v[190:191] op_sel_hi:[1,0]
	v_pk_mul_f32 v[54:55], v[54:55], v[190:191] op_sel_hi:[1,0]
	v_pk_mul_f32 v[48:49], v[48:49], v[190:191] op_sel_hi:[1,0]
	v_pk_mul_f32 v[50:51], v[50:51], v[190:191] op_sel_hi:[1,0]
	v_max_f32_e32 v52, 0, v52
	v_max_f32_e32 v53, 0, v53
	v_max_f32_e32 v54, 0, v54
	v_max_f32_e32 v55, 0, v55
	v_max_f32_e32 v48, 0, v48
	v_max_f32_e32 v49, 0, v49
	v_max_f32_e32 v50, 0, v50
	v_max_f32_e32 v51, 0, v51
	v_pk_mul_f32 v[52:53], v[52:53], v[52:53]
	v_pk_mul_f32 v[54:55], v[54:55], v[54:55]
	v_pk_mul_f32 v[48:49], v[48:49], v[48:49]
;     __device__ __forceinline__ void operator()(const f32x4 (&acc)[2][2][4][2], const pg8::Unit& u, int wr, int wc, int fr, int fq) const {
;     ...
;         for (int ai = 0; ai < 2; ++ai)
; #pragma unroll
;             for (int m = 0; m < 4; ++m) {
;                 const int row = row0 + ai * 128 + m * 16;
;                 float ss = 0.f, rstd = 1.f;
;                 if (MODE == 2) rstd = rsqrtf(rowss[row] * (1.f / 1024.f) + EPS);
; #pragma unroll
;                 for (int bj = 0; bj < 2; ++bj) {
;                     const int c = col0 + bj * 128;
;                     f32x4 v0 = acc[ai][bj][m][0], v1 = acc[ai][bj][m][1];
;                     if (MODE == 1) {
;                         const float* rp = res + (size_t)row * ldres + c;
;                         v0 += *(const f32x4*)rp; v1 += *(const f32x4*)(rp + 4);
;                     }
;                     if (MODE == 3) {
;                         const h16x8 r8 = *(const h16x8*)(res16 + (size_t)row * ldres + c);
; #pragma unroll
;                         for (int j = 0; j < 4; ++j) { v0[j] += (float)r8[j]; v1[j] += (float)r8[4 + j]; }
;                     }
;                     if (MODE == 1 || MODE == 3) {
;                         ss += v0[0] * v0[0] + v0[1] * v0[1] + v0[2] * v0[2] + v0[3] * v0[3] + v1[0] * v1[0] + v1[1] * v1[1] + v1[2] * v1[2] + v1[3] * v1[3];
;                     }
;                     if (MODE == 2) {
; #pragma unroll
;                         for (int j = 0; j < 4; ++j) { float a = fmaxf(v0[j] * rstd, 0.f), b = fmaxf(v1[j] * rstd, 0.f); v0[j] = a * a; v1[j] = b * b; }
;                     }
;                     *(h16x8*)(o16 + (size_t)row * ld16 + c) = pack8(v0, v1);
	v_pk_mul_f32 v[50:51], v[50:51], v[50:51]
	v_cvt_pk_f16_f32 v52, v52, v53
	v_cvt_pk_f16_f32 v53, v54, v55
	v_cvt_pk_f16_f32 v54, v48, v49
	v_cvt_pk_f16_f32 v55, v50, v51
	s_nop 1
	v_mov_b32_dpp v192, v52 row_ror:8 row_mask:0xf bank_mask:0xf
	v_mov_b32_dpp v193, v53 row_ror:8 row_mask:0xf bank_mask:0xf
	v_mov_b32_dpp v194, v54 row_ror:8 row_mask:0xf bank_mask:0xf
	v_mov_b32_dpp v195, v55 row_ror:8 row_mask:0xf bank_mask:0xf
	v_cndmask_b32_e64 v52, v192, v60, s[98:99]
	v_cndmask_b32_e64 v53, v193, v61, s[98:99]
	v_cndmask_b32_e64 v54, v194, v62, s[98:99]
	v_cndmask_b32_e64 v55, v195, v63, s[98:99]
	v_cndmask_b32_e64 v192, v60, v192, s[98:99]
	v_cndmask_b32_e64 v193, v61, v193, s[98:99]
	v_cndmask_b32_e64 v194, v62, v194, s[98:99]
	v_cndmask_b32_e64 v195, v63, v195, s[98:99]
	v_lshl_add_u64 v[196:197], v[164:165], 0, v[214:215]
	v_lshl_add_u64 v[198:199], v[164:165], 0, v[216:217]
	global_store_dwordx4 v[196:197], v[52:55], off sc0 sc1
	global_store_dwordx4 v[198:199], v[192:195], off sc0 sc1
	s_mov_b32 s100, 0x20000
	s_mov_b32 s101, 0
	v_lshl_add_u64 v[164:165], v[164:165], 0, s[100:101]
	v_fmamk_f32 v190, v186, 0x3a800000, v213
	v_mul_f32_e32 v191, 0x4b800000, v190
	v_cmp_gt_f32_e64 s[100:101], s53, v190
	s_nop 1
	v_cndmask_b32_e64 v190, v190, v191, s[100:101]
	v_rsq_f32_e32 v190, v190
	s_nop 0
	v_mul_f32_e32 v191, 0x45800000, v190
	v_cndmask_b32_e64 v190, v190, v191, s[100:101]
	v_pk_mul_f32 v[44:45], v[44:45], v[190:191] op_sel_hi:[1,0]
	v_pk_mul_f32 v[46:47], v[46:47], v[190:191] op_sel_hi:[1,0]
	v_pk_mul_f32 v[40:41], v[40:41], v[190:191] op_sel_hi:[1,0]
	v_pk_mul_f32 v[42:43], v[42:43], v[190:191] op_sel_hi:[1,0]
	v_max_f32_e32 v44, 0, v44
	v_max_f32_e32 v45, 0, v45
	v_max_f32_e32 v46, 0, v46
	v_max_f32_e32 v47, 0, v47
	v_max_f32_e32 v40, 0, v40
	v_max_f32_e32 v41, 0, v41
	v_max_f32_e32 v42, 0, v42
	v_max_f32_e32 v43, 0, v43
	v_pk_mul_f32 v[44:45], v[44:45], v[44:45]
	v_pk_mul_f32 v[46:47], v[46:47], v[46:47]
	v_pk_mul_f32 v[40:41], v[40:41], v[40:41]
	v_pk_mul_f32 v[42:43], v[42:43], v[42:43]
	v_cvt_pk_f16_f32 v44, v44, v45
	v_cvt_pk_f16_f32 v45, v46, v47
	v_cvt_pk_f16_f32 v46, v40, v41
	v_cvt_pk_f16_f32 v47, v42, v43
	v_pk_mul_f32 v[36:37], v[36:37], v[190:191] op_sel_hi:[1,0]
	v_pk_mul_f32 v[38:39], v[38:39], v[190:191] op_sel_hi:[1,0]
	v_pk_mul_f32 v[32:33], v[32:33], v[190:191] op_sel_hi:[1,0]
	v_pk_mul_f32 v[34:35], v[34:35], v[190:191] op_sel_hi:[1,0]
	v_max_f32_e32 v36, 0, v36
	v_max_f32_e32 v37, 0, v37
	v_max_f32_e32 v38, 0, v38
	v_max_f32_e32 v39, 0, v39
	v_max_f32_e32 v32, 0, v32
	v_max_f32_e32 v33, 0, v33
	v_max_f32_e32 v34, 0, v34
	v_max_f32_e32 v35, 0, v35
	v_pk_mul_f32 v[36:37], v[36:37], v[36:37]
	v_pk_mul_f32 v[38:39], v[38:39], v[38:39]
	v_pk_mul_f32 v[32:33], v[32:33], v[32:33]
	v_pk_mul_f32 v[34:35], v[34:35], v[34:35]
	v_cvt_pk_f16_f32 v36, v36, v37
	v_cvt_pk_f16_f32 v37, v38, v39
	v_cvt_pk_f16_f32 v38, v32, v33
	v_cvt_pk_f16_f32 v39, v34, v35
	s_nop 1
	v_mov_b32_dpp v204, v36 row_ror:8 row_mask:0xf bank_mask:0xf
	v_mov_b32_dpp v205, v37 row_ror:8 row_mask:0xf bank_mask:0xf
	v_mov_b32_dpp v206, v38 row_ror:8 row_mask:0xf bank_mask:0xf
	v_mov_b32_dpp v207, v39 row_ror:8 row_mask:0xf bank_mask:0xf
	v_cndmask_b32_e64 v36, v204, v44, s[98:99]
	v_cndmask_b32_e64 v37, v205, v45, s[98:99]
	v_cndmask_b32_e64 v38, v206, v46, s[98:99]
	v_cndmask_b32_e64 v39, v207, v47, s[98:99]
	v_cndmask_b32_e64 v204, v44, v204, s[98:99]
	v_cndmask_b32_e64 v205, v45, v205, s[98:99]
	v_cndmask_b32_e64 v206, v46, v206, s[98:99]
	v_cndmask_b32_e64 v207, v47, v207, s[98:99]
	v_lshl_add_u64 v[208:209], v[164:165], 0, v[214:215]
	v_lshl_add_u64 v[210:211], v[164:165], 0, v[216:217]
	global_store_dwordx4 v[208:209], v[36:39], off sc0 sc1
	global_store_dwordx4 v[210:211], v[204:207], off sc0 sc1
	s_mov_b32 s100, 0x20000
	s_mov_b32 s101, 0
	v_lshl_add_u64 v[164:165], v[164:165], 0, s[100:101]
	v_fmamk_f32 v190, v187, 0x3a800000, v213
	v_mul_f32_e32 v191, 0x4b800000, v190
	v_cmp_gt_f32_e64 s[100:101], s53, v190
	s_nop 1
	v_cndmask_b32_e64 v190, v190, v191, s[100:101]
	v_rsq_f32_e32 v190, v190
	s_nop 0
	v_mul_f32_e32 v191, 0x45800000, v190
	v_cndmask_b32_e64 v190, v190, v191, s[100:101]
	v_pk_mul_f32 v[28:29], v[28:29], v[190:191] op_sel_hi:[1,0]
	v_pk_mul_f32 v[30:31], v[30:31], v[190:191] op_sel_hi:[1,0]
	v_pk_mul_f32 v[24:25], v[24:25], v[190:191] op_sel_hi:[1,0]
	v_pk_mul_f32 v[26:27], v[26:27], v[190:191] op_sel_hi:[1,0]
	v_max_f32_e32 v28, 0, v28
	v_max_f32_e32 v29, 0, v29
	v_max_f32_e32 v30, 0, v30
	v_max_f32_e32 v31, 0, v31
	v_max_f32_e32 v24, 0, v24
	v_max_f32_e32 v25, 0, v25
	v_max_f32_e32 v26, 0, v26
	v_max_f32_e32 v27, 0, v27
	v_pk_mul_f32 v[28:29], v[28:29], v[28:29]
; #define PG8_WAIT_V(n) asm volatile("s_waitcnt vmcnt(" #n ")" ::: "memory")
; #define PG8_BAR __builtin_amdgcn_s_barrier()
; template <class Epi>
; __device__ __forceinline__ void gemm_phase(LAS unsigned char* lds, const Gemm g, const StaticOrder& S, const Epi& E) {
;     ...
;         if (!has_next) break;
; #pragma unroll
;         for (int a = 0; a < 2; ++a)
; #pragma unroll
;             for (int b = 0; b < 2; ++b)
; #pragma unroll
;                 for (int m = 0; m < 4; ++m)
; #pragma unroll
;                     for (int n = 0; n < 2; ++n) acc[a][b][m][n] = (f32x4){0.f, 0.f, 0.f, 0.f};
;         cur = nxt; cA = nA; cB = nB; ++ui;
;     }
;     PG8_WAIT_V(0);
;     if (wr == 0) PG8_BAR;
;     PG8_BAR;
;     __device__ __forceinline__ void operator()(const f32x4 (&acc)[2][2][4][2], const pg8::Unit& u, int wr, int wc, int fr, int fq) const {
;     ...
;         for (int ai = 0; ai < 2; ++ai)
; #pragma unroll
;             for (int m = 0; m < 4; ++m) {
;                 const int row = row0 + ai * 128 + m * 16;
;                 float ss = 0.f, rstd = 1.f;
;                 if (MODE == 2) rstd = rsqrtf(rowss[row] * (1.f / 1024.f) + EPS);
; #pragma unroll
;                 for (int bj = 0; bj < 2; ++bj) {
;                     const int c = col0 + bj * 128;
;                     f32x4 v0 = acc[ai][bj][m][0], v1 = acc[ai][bj][m][1];
;                     if (MODE == 1) {
;                         const float* rp = res + (size_t)row * ldres + c;
;                         v0 += *(const f32x4*)rp; v1 += *(const f32x4*)(rp + 4);
;                     }
;                     if (MODE == 3) {
;                         const h16x8 r8 = *(const h16x8*)(res16 + (size_t)row * ldres + c);
; #pragma unroll
;                         for (int j = 0; j < 4; ++j) { v0[j] += (float)r8[j]; v1[j] += (float)r8[4 + j]; }
;                     }
;                     if (MODE == 1 || MODE == 3) {
;                         ss += v0[0] * v0[0] + v0[1] * v0[1] + v0[2] * v0[2] + v0[3] * v0[3] + v1[0] * v1[0] + v1[1] * v1[1] + v1[2] * v1[2] + v1[3] * v1[3];
;                     }
;                     if (MODE == 2) {
; #pragma unroll
;                         for (int j = 0; j < 4; ++j) { float a = fmaxf(v0[j] * rstd, 0.f), b = fmaxf(v1[j] * rstd, 0.f); v0[j] = a * a; v1[j] = b * b; }
;                     }
;                     *(h16x8*)(o16 + (size_t)row * ld16 + c) = pack8(v0, v1);
	v_pk_mul_f32 v[30:31], v[30:31], v[30:31]
	v_pk_mul_f32 v[24:25], v[24:25], v[24:25]
	v_pk_mul_f32 v[26:27], v[26:27], v[26:27]
	v_cvt_pk_f16_f32 v28, v28, v29
	v_cvt_pk_f16_f32 v29, v30, v31
	v_cvt_pk_f16_f32 v30, v24, v25
	v_cvt_pk_f16_f32 v31, v26, v27
	v_pk_mul_f32 v[20:21], v[20:21], v[190:191] op_sel_hi:[1,0]
	v_pk_mul_f32 v[22:23], v[22:23], v[190:191] op_sel_hi:[1,0]
	v_pk_mul_f32 v[16:17], v[16:17], v[190:191] op_sel_hi:[1,0]
	v_pk_mul_f32 v[18:19], v[18:19], v[190:191] op_sel_hi:[1,0]
	v_max_f32_e32 v20, 0, v20
	v_max_f32_e32 v21, 0, v21
	v_max_f32_e32 v22, 0, v22
	v_max_f32_e32 v23, 0, v23
	v_max_f32_e32 v16, 0, v16
	v_max_f32_e32 v17, 0, v17
	v_max_f32_e32 v18, 0, v18
	v_max_f32_e32 v19, 0, v19
	v_pk_mul_f32 v[20:21], v[20:21], v[20:21]
	v_pk_mul_f32 v[22:23], v[22:23], v[22:23]
	v_pk_mul_f32 v[16:17], v[16:17], v[16:17]
	v_pk_mul_f32 v[18:19], v[18:19], v[18:19]
	v_cvt_pk_f16_f32 v20, v20, v21
	v_cvt_pk_f16_f32 v21, v22, v23
	v_cvt_pk_f16_f32 v22, v16, v17
	v_cvt_pk_f16_f32 v23, v18, v19
	s_nop 1
	v_mov_b32_dpp v192, v20 row_ror:8 row_mask:0xf bank_mask:0xf
	v_mov_b32_dpp v193, v21 row_ror:8 row_mask:0xf bank_mask:0xf
	v_mov_b32_dpp v194, v22 row_ror:8 row_mask:0xf bank_mask:0xf
	v_mov_b32_dpp v195, v23 row_ror:8 row_mask:0xf bank_mask:0xf
	v_cndmask_b32_e64 v20, v192, v28, s[98:99]
	v_cndmask_b32_e64 v21, v193, v29, s[98:99]
	v_cndmask_b32_e64 v22, v194, v30, s[98:99]
	v_cndmask_b32_e64 v23, v195, v31, s[98:99]
	v_cndmask_b32_e64 v192, v28, v192, s[98:99]
	v_cndmask_b32_e64 v193, v29, v193, s[98:99]
	v_cndmask_b32_e64 v194, v30, v194, s[98:99]
	v_cndmask_b32_e64 v195, v31, v195, s[98:99]
	v_lshl_add_u64 v[196:197], v[164:165], 0, v[214:215]
	v_lshl_add_u64 v[198:199], v[164:165], 0, v[216:217]
	global_store_dwordx4 v[196:197], v[20:23], off sc0 sc1
	global_store_dwordx4 v[198:199], v[192:195], off sc0 sc1
	s_mov_b32 s100, 0x20000
	s_mov_b32 s101, 0
	v_lshl_add_u64 v[164:165], v[164:165], 0, s[100:101]
	v_fmamk_f32 v190, v188, 0x3a800000, v213
	v_mul_f32_e32 v191, 0x4b800000, v190
	v_cmp_gt_f32_e64 s[100:101], s53, v190
	s_nop 1
	v_cndmask_b32_e64 v190, v190, v191, s[100:101]
	v_rsq_f32_e32 v190, v190
	s_nop 0
	v_mul_f32_e32 v191, 0x45800000, v190
	v_cndmask_b32_e64 v190, v190, v191, s[100:101]
	v_pk_mul_f32 v[12:13], v[12:13], v[190:191] op_sel_hi:[1,0]
	v_pk_mul_f32 v[14:15], v[14:15], v[190:191] op_sel_hi:[1,0]
	v_pk_mul_f32 v[8:9], v[8:9], v[190:191] op_sel_hi:[1,0]
	v_pk_mul_f32 v[10:11], v[10:11], v[190:191] op_sel_hi:[1,0]
	v_max_f32_e32 v12, 0, v12
	v_max_f32_e32 v13, 0, v13
	v_max_f32_e32 v14, 0, v14
	v_max_f32_e32 v15, 0, v15
	v_max_f32_e32 v8, 0, v8
	v_max_f32_e32 v9, 0, v9
	v_max_f32_e32 v10, 0, v10
	v_max_f32_e32 v11, 0, v11
	v_pk_mul_f32 v[12:13], v[12:13], v[12:13]
	v_pk_mul_f32 v[14:15], v[14:15], v[14:15]
	v_pk_mul_f32 v[8:9], v[8:9], v[8:9]
	v_pk_mul_f32 v[10:11], v[10:11], v[10:11]
	v_cvt_pk_f16_f32 v12, v12, v13
	v_cvt_pk_f16_f32 v13, v14, v15
	v_cvt_pk_f16_f32 v14, v8, v9
	v_cvt_pk_f16_f32 v15, v10, v11
	v_pk_mul_f32 v[4:5], v[4:5], v[190:191] op_sel_hi:[1,0]
	v_pk_mul_f32 v[6:7], v[6:7], v[190:191] op_sel_hi:[1,0]
	v_pk_mul_f32 v[0:1], v[0:1], v[190:191] op_sel_hi:[1,0]
	v_pk_mul_f32 v[2:3], v[2:3], v[190:191] op_sel_hi:[1,0]
	v_max_f32_e32 v4, 0, v4
	v_max_f32_e32 v5, 0, v5
	v_max_f32_e32 v6, 0, v6
	v_max_f32_e32 v7, 0, v7
	v_max_f32_e32 v0, 0, v0
	v_max_f32_e32 v1, 0, v1
	v_max_f32_e32 v2, 0, v2
	v_max_f32_e32 v3, 0, v3
	v_pk_mul_f32 v[4:5], v[4:5], v[4:5]
	v_pk_mul_f32 v[6:7], v[6:7], v[6:7]
	v_pk_mul_f32 v[0:1], v[0:1], v[0:1]
	v_pk_mul_f32 v[2:3], v[2:3], v[2:3]
	v_cvt_pk_f16_f32 v4, v4, v5
	v_cvt_pk_f16_f32 v5, v6, v7
	v_cvt_pk_f16_f32 v6, v0, v1
	v_cvt_pk_f16_f32 v7, v2, v3
	s_nop 1
	v_mov_b32_dpp v204, v4 row_ror:8 row_mask:0xf bank_mask:0xf
	v_mov_b32_dpp v205, v5 row_ror:8 row_mask:0xf bank_mask:0xf
	v_mov_b32_dpp v206, v6 row_ror:8 row_mask:0xf bank_mask:0xf
	v_mov_b32_dpp v207, v7 row_ror:8 row_mask:0xf bank_mask:0xf
	v_cndmask_b32_e64 v4, v204, v12, s[98:99]
	v_cndmask_b32_e64 v5, v205, v13, s[98:99]
	v_cndmask_b32_e64 v6, v206, v14, s[98:99]
	v_cndmask_b32_e64 v7, v207, v15, s[98:99]
	v_cndmask_b32_e64 v204, v12, v204, s[98:99]
	v_cndmask_b32_e64 v205, v13, v205, s[98:99]
	v_cndmask_b32_e64 v206, v14, v206, s[98:99]
	v_cndmask_b32_e64 v207, v15, v207, s[98:99]
	v_lshl_add_u64 v[208:209], v[164:165], 0, v[214:215]
	v_lshl_add_u64 v[210:211], v[164:165], 0, v[216:217]
	global_store_dwordx4 v[208:209], v[4:7], off sc0 sc1
	global_store_dwordx4 v[210:211], v[204:207], off sc0 sc1
	s_and_b64 vcc, exec, s[6:7]
	s_cbranch_vccz .LBB0_476
	s_waitcnt vmcnt(0)
	s_cmpk_gt_u32 s41, 0xff
	s_cbranch_scc1 .LBB0_487
	s_barrier

; __device__ __forceinline__ f32x4 mfma16(h16x8 a, h16x8 b, f32x4 c) { return __builtin_amdgcn_mfma_f32_16x16x32_f16(a, b, c, 0, 0, 0); }
; template <int MODE>
; __device__ __forceinline__ void skinny(const Params& p, const h16* A, int lda, int row0, int nrt, const h16* Bt, int K, int nct) {
;     ...
;     for (int task = gw; task < nrt * nct; task += ngw) {
;         const int rt = task % nrt, ct = task / nrt;
;         const h16* ap = A + (size_t)(row0 + rt * 16 + fr) * lda + fq * 8;
;         const h16* bp = Bt + (size_t)(ct * 16 + fr) * K + fq * 8;
;         f32x4 acc = {0.f, 0.f, 0.f, 0.f};
; #pragma unroll 8
;         for (int k = 0; k < K; k += 32) { const h16x8 a = *(const h16x8*)(ap + k); const h16x8 b = *(const h16x8*)(bp + k); acc = mfma16(b, a, acc); }
.LBB0_490:
	v_ashrrev_i32_e32 v0, 31, v11
	v_lshrrev_b32_e32 v0, 29, v0
	v_add_u32_e32 v2, v11, v0
	v_and_b32_e32 v0, 0xffffff8, v2
	v_lshlrev_b32_e32 v2, 1, v2
	s_waitcnt vmcnt(0)
	v_and_b32_e32 v12, -16, v2
	v_sub_u32_e32 v0, v11, v0
	v_or_b32_e32 v2, v12, v131
	v_and_b32_e32 v14, 0xe0, v2
	v_lshrrev_b32_e32 v15, 1, v14
	v_lshlrev_b32_e32 v14, 2, v14
	v_and_b32_e32 v14, 0x80, v14
	v_and_b32_e32 v15, 0x60, v15
	v_or_b32_e32 v15, v15, v14
	v_and_b32_e32 v2, 0xffffff1f, v2
	v_or_b32_e32 v2, v2, v15
	v_lshl_add_u32 v4, v0, 4, v137
	v_ashrrev_i32_e32 v3, 31, v2
	v_lshlrev_b64 v[0:1], 11, v[4:5]
	v_lshlrev_b64 v[2:3], 11, v[2:3]
	v_lshl_add_u64 v[6:7], s[82:83], 0, v[0:1]
	v_lshl_add_u64 v[8:9], s[82:83], 0, v[2:3]
	s_movk_i32 s0, 0xffe0
	v_mov_b32_e32 v0, v5
	v_mov_b32_e32 v1, v5
	v_mov_b32_e32 v2, v5
	v_mov_b32_e32 v3, v5
